# scan v2b + NSA sel-branch LDS-read hoist + top-k scalar compare (SALU instead of VALU-on-SGPR per radix bit)
# speedup vs baseline: 1.0085x; 1.0060x over previous
; __device__ __forceinline__ void nsa_unit(const Args& a, int l, int b, int qi, float bnd0, float bnd1, float bnd2, LAS unsigned char* lds, int tid, int lane, int wave) {
;     ...
;         for (int qq = 0; qq < 8; ++qq) { const int q = wave * 8 + qq, j = lane;
;             const float v = (IMP[q * 65 + j] * INVL[q] + IMP[4160 + q * 65 + j] * INVL[64 + q]) + (IMP[8320 + q * 65 + j] * INVL[128 + q] + IMP[12480 + q * 65 + j] * INVL[192 + q]);
;             const bool forced = (j == 0) || (j == qi) || (j == qi - 1);
;             const float val = (j <= qi) ? v + (forced ? 1e4f : 0.f) : -1.0f;
;             const unsigned ub = __float_as_uint(val), key = (ub & 0x80000000u) ? ~ub : (ub | 0x80000000u);
;             unsigned prefix = 0u;
; #pragma unroll
;     ...
;             const unsigned long long gtm = __ballot(key > prefix), eqm = __ballot(key == prefix);
;             const int need = 16 - __builtin_popcountll(gtm);
;             const bool pick = (key > prefix) || (key == prefix && __builtin_popcountll(eqm & ((1ull << lane) - 1ull)) < need);
;             unsigned long long m = __ballot(pick);
;             m &= (qi == 63) ? ~0ull : ((1ull << (qi + 1)) - 1ull);
;             if (lane == 0) SELM[q] = m;
.LBB0_186:
	s_add_i32 s46, s23, 0
	v_add_u32_e32 v62, 0, v59
	s_add_i32 s47, s46, 0x19a40
	ds_read2st64_b32 v[60:61], v62 offset0:148 offset1:213
	v_mov_b32_e32 v63, s47
	s_add_i32 s47, s46, 0x19b40
	s_waitcnt vmcnt(1)
	v_mov_b32_e32 v64, s47
	v_add_u32_e32 v65, 0x11600, v62
	s_add_i32 s47, s46, 0x19c40
	s_add_i32 s46, s46, 0x19d40
	v_mov_b32_e32 v66, s47
	s_waitcnt vmcnt(0)
	v_add_u32_e32 v68, 0x15700, v62
	v_mov_b32_e32 v70, s46
	ds_read_b32 v62, v63
	ds_read_b32 v64, v64
	ds_read_b32 v67, v65
	ds_read_b32 v69, v68
	ds_read_b32 v65, v70
	ds_read_b32 v63, v66
	s_waitcnt lgkmcnt(6)
	v_mov_b32_e32 v68, v61
	v_mov_b32_e32 v66, v60
	s_waitcnt lgkmcnt(1)
	v_pk_mul_f32 v[60:61], v[68:69], v[64:65]
	s_waitcnt lgkmcnt(0)
	v_pk_fma_f32 v[60:61], v[66:67], v[62:63], v[60:61]
	s_nop 0
	v_add_f32_e32 v60, v60, v61
	v_add_f32_e32 v60, v58, v60
	v_cndmask_b32_e64 v60, v60, -1.0, vcc
	v_not_b32_e32 v61, v60
	v_cmp_gt_i32_e64 s[46:47], 0, v60
	s_nop 1
	v_cndmask_b32_e64 v60, -|v60|, v61, s[46:47]
	v_cmp_gt_i32_e64 s[46:47], 0, v60
	s_bcnt1_i32_b64 s96, s[46:47]
	s_cmp_gt_u32 s96, 15
	s_cselect_b32 s48, 0x80000000, 0
	s_or_b32 s49, s48, 2.0
	v_cmp_le_u32_e64 s[46:47], s49, v60
	s_bcnt1_i32_b64 s96, s[46:47]
	s_cmp_gt_u32 s96, 15
	s_cselect_b32 s48, s49, s48
	s_or_b32 s49, s48, 0x20000000
	v_cmp_le_u32_e64 s[46:47], s49, v60
	s_bcnt1_i32_b64 s96, s[46:47]
	s_cmp_gt_u32 s96, 15
	s_cselect_b32 s48, s49, s48
	s_or_b32 s49, s48, 0x10000000
	v_cmp_le_u32_e64 s[46:47], s49, v60
	s_bcnt1_i32_b64 s96, s[46:47]
	s_cmp_gt_u32 s96, 15
	s_cselect_b32 s48, s49, s48
	s_or_b32 s49, s48, 0x8000000
	v_cmp_le_u32_e64 s[46:47], s49, v60
	s_bcnt1_i32_b64 s96, s[46:47]
	s_cmp_gt_u32 s96, 15
	s_cselect_b32 s48, s49, s48
	s_or_b32 s49, s48, 0x4000000
	v_cmp_le_u32_e64 s[46:47], s49, v60
	s_bcnt1_i32_b64 s96, s[46:47]
	s_cmp_gt_u32 s96, 15
	s_cselect_b32 s48, s49, s48
	s_or_b32 s49, s48, 0x2000000
	v_cmp_le_u32_e64 s[46:47], s49, v60
	s_bcnt1_i32_b64 s96, s[46:47]
	s_cmp_gt_u32 s96, 15
	s_cselect_b32 s48, s49, s48
	s_or_b32 s49, s48, 0x1000000
	v_cmp_le_u32_e64 s[46:47], s49, v60
	s_bcnt1_i32_b64 s96, s[46:47]
	s_cmp_gt_u32 s96, 15
	s_cselect_b32 s48, s49, s48
	s_or_b32 s49, s48, 0x800000
	v_cmp_le_u32_e64 s[46:47], s49, v60
	s_bcnt1_i32_b64 s96, s[46:47]
	s_cmp_gt_u32 s96, 15
	s_cselect_b32 s48, s49, s48
	s_or_b32 s49, s48, 0x400000
	v_cmp_le_u32_e64 s[46:47], s49, v60
	s_bcnt1_i32_b64 s96, s[46:47]
	s_cmp_gt_u32 s96, 15
	s_cselect_b32 s48, s49, s48
	s_or_b32 s49, s48, 0x200000
	v_cmp_le_u32_e64 s[46:47], s49, v60
	s_bcnt1_i32_b64 s96, s[46:47]
	s_cmp_gt_u32 s96, 15
	s_cselect_b32 s48, s49, s48
	s_or_b32 s49, s48, 0x100000
	v_cmp_le_u32_e64 s[46:47], s49, v60
	s_bcnt1_i32_b64 s96, s[46:47]
	s_cmp_gt_u32 s96, 15
	s_cselect_b32 s48, s49, s48
	s_or_b32 s49, s48, 0x80000
	v_cmp_le_u32_e64 s[46:47], s49, v60
	s_bcnt1_i32_b64 s96, s[46:47]
	s_cmp_gt_u32 s96, 15
	s_cselect_b32 s48, s49, s48
	s_or_b32 s49, s48, 0x40000
	v_cmp_le_u32_e64 s[46:47], s49, v60
	s_bcnt1_i32_b64 s96, s[46:47]
	s_cmp_gt_u32 s96, 15
	s_cselect_b32 s48, s49, s48
	s_or_b32 s49, s48, 0x20000
	v_cmp_le_u32_e64 s[46:47], s49, v60
	s_bcnt1_i32_b64 s96, s[46:47]
	s_cmp_gt_u32 s96, 15
	s_cselect_b32 s48, s49, s48
	s_or_b32 s49, s48, 0x10000
	v_cmp_le_u32_e64 s[46:47], s49, v60
	s_bcnt1_i32_b64 s96, s[46:47]
	s_cmp_gt_u32 s96, 15
	s_cselect_b32 s48, s49, s48
	s_or_b32 s49, s48, 0x8000
	v_cmp_le_u32_e64 s[46:47], s49, v60
	s_bcnt1_i32_b64 s96, s[46:47]
	s_cmp_gt_u32 s96, 15
	s_cselect_b32 s48, s49, s48
	s_or_b32 s49, s48, 0x4000
	v_cmp_le_u32_e64 s[46:47], s49, v60
	s_bcnt1_i32_b64 s96, s[46:47]
	s_cmp_gt_u32 s96, 15
	s_cselect_b32 s48, s49, s48
	s_or_b32 s49, s48, 0x2000
	v_cmp_le_u32_e64 s[46:47], s49, v60
	s_bcnt1_i32_b64 s96, s[46:47]
	s_cmp_gt_u32 s96, 15
	s_cselect_b32 s48, s49, s48
	s_or_b32 s49, s48, 0x1000
	v_cmp_le_u32_e64 s[46:47], s49, v60
	s_bcnt1_i32_b64 s96, s[46:47]
	s_cmp_gt_u32 s96, 15
	s_cselect_b32 s48, s49, s48
	s_or_b32 s49, s48, 0x800
	v_cmp_le_u32_e64 s[46:47], s49, v60
	s_bcnt1_i32_b64 s96, s[46:47]
	s_cmp_gt_u32 s96, 15
	s_cselect_b32 s48, s49, s48
	s_or_b32 s49, s48, 0x400
	v_cmp_le_u32_e64 s[46:47], s49, v60
	s_bcnt1_i32_b64 s96, s[46:47]
	s_cmp_gt_u32 s96, 15
	s_cselect_b32 s48, s49, s48
	s_or_b32 s49, s48, 0x200
	v_cmp_le_u32_e64 s[46:47], s49, v60
	s_bcnt1_i32_b64 s96, s[46:47]
	s_cmp_gt_u32 s96, 15
	s_cselect_b32 s48, s49, s48
	s_or_b32 s49, s48, 0x100
	v_cmp_le_u32_e64 s[46:47], s49, v60
	s_bcnt1_i32_b64 s96, s[46:47]
	s_cmp_gt_u32 s96, 15
	s_cselect_b32 s48, s49, s48
	s_or_b32 s49, s48, 0x80
	v_cmp_le_u32_e64 s[46:47], s49, v60
	s_bcnt1_i32_b64 s96, s[46:47]
	s_cmp_gt_u32 s96, 15
	s_cselect_b32 s48, s49, s48
	s_or_b32 s49, s48, 64
	v_cmp_le_u32_e64 s[46:47], s49, v60
	s_bcnt1_i32_b64 s96, s[46:47]
	s_cmp_gt_u32 s96, 15
	s_cselect_b32 s48, s49, s48
	s_or_b32 s49, s48, 32
	v_cmp_le_u32_e64 s[46:47], s49, v60
	s_bcnt1_i32_b64 s96, s[46:47]
	s_cmp_gt_u32 s96, 15
	s_cselect_b32 s48, s49, s48
	s_or_b32 s49, s48, 16
	v_cmp_le_u32_e64 s[46:47], s49, v60
	s_bcnt1_i32_b64 s96, s[46:47]
	s_cmp_gt_u32 s96, 15
	s_cselect_b32 s48, s49, s48
	s_or_b32 s49, s48, 8
	v_cmp_le_u32_e64 s[46:47], s49, v60
	s_bcnt1_i32_b64 s96, s[46:47]
	s_cmp_gt_u32 s96, 15
	s_cselect_b32 s48, s49, s48
	s_or_b32 s49, s48, 4
	v_cmp_le_u32_e64 s[46:47], s49, v60
	s_bcnt1_i32_b64 s96, s[46:47]
	s_cmp_gt_u32 s96, 15
	s_cselect_b32 s48, s49, s48
	s_or_b32 s49, s48, 2
	v_cmp_le_u32_e64 s[46:47], s49, v60
	s_bcnt1_i32_b64 s96, s[46:47]
	s_cmp_gt_u32 s96, 15
	s_cselect_b32 s48, s49, s48
	s_or_b32 s49, s48, 1
	v_cmp_le_u32_e64 s[46:47], s49, v60
	s_bcnt1_i32_b64 s96, s[46:47]
	s_cmp_gt_u32 s96, 15
	s_cselect_b32 s48, s49, s48
	v_cmp_lt_u32_e64 s[46:47], s48, v60
	v_cmp_eq_u32_e64 s[48:49], s48, v60
	s_nop 0
	v_cndmask_b32_e64 v61, 0, 1, s[46:47]
	v_and_b32_e32 v62, s48, v138
	s_bcnt1_i32_b64 s46, s[46:47]
	v_and_b32_e32 v60, s49, v127
	v_bcnt_u32_b32 v62, v62, 0
	s_sub_i32 s46, 16, s46
	v_bcnt_u32_b32 v60, v60, v62
	v_cmp_gt_i32_e64 s[46:47], s46, v60
	s_nop 1
	v_cndmask_b32_e64 v60, 0, 1, s[46:47]
	v_cndmask_b32_e64 v60, v61, v60, s[48:49]
	v_and_b32_e32 v60, 1, v60
	v_cmp_ne_u32_e64 s[46:47], 0, v60
	s_and_b64 s[46:47], s[46:47], s[52:53]
	s_and_saveexec_b64 s[48:49], s[44:45]
	s_cbranch_execz .LBB0_185
	s_add_i32 s55, s54, 0
	v_mov_b32_e32 v60, s55
	v_mov_b64_e32 v[62:63], s[46:47]
	ds_write_b64 v60, v[62:63]
	s_branch .LBB0_185
